# P0: forget-gate lower-bound logits loaded at phase start (workgroup 0 no longer ends P0 with a cold round trip)
# baseline (speedup 1.0000x reference)
; __device__ __forceinline__ void conv_load(float (&wv)[32], const float* W, int N, int kb, int nb_src, int lane) {
;     const int k0 = 64 * kb, n0 = 32 * nb_src;
; #pragma unroll
;     for (int i = 0; i < 32; ++i) { const int kk = 2 * i + (lane >> 5); wv[i] = __builtin_nontemporal_load(&W[(size_t)(k0 + kk) * N + n0 + (lane & 31)]); }
; __global__ void __launch_bounds__(NT, 2) hymba_fwd(Args args) {
;     ...
;         if (bid == 0) { const float* lg = args.in[7]; LBv[tid] = 1.0f / (1.0f + __expf(lg[512 + tid] - lg[tid])); }
.LBB0_17:
	s_lshr_b32 s2, s71, 6
	v_writelane_b32 v237, s2, 6
	s_load_dwordx2 s[2:3], s[0:1], 0x80
	v_and_b32_e32 v178, 63, v179
	s_waitcnt lgkmcnt(0)
	s_add_u32 s10, s2, 0x800000
	s_addc_u32 s11, s3, 0
	s_cmp_lt_i32 s76, 1
	s_cselect_b64 s[2:3], -1, 0
	s_cmp_gt_i32 s77, 0
	s_cselect_b64 s[4:5], -1, 0
	s_and_b64 s[2:3], s[2:3], s[4:5]
	s_andn2_b64 vcc, exec, s[2:3]
	s_cbranch_vccnz .LBB0_151
	v_lshlrev_b32_e32 v90, 2, v179
	global_load_dword v91, v90, s[26:27] offset:2048
	global_load_dword v92, v90, s[26:27]
	s_lshl_b32 s4, s68, 3
	v_readlane_b32 s5, v237, 6
	s_add_i32 s30, s5, s4
	s_cmpk_lt_i32 s30, 0xb00
	s_cselect_b64 s[4:5], -1, 0
	s_cmpk_gt_i32 s30, 0xaff
	s_cbranch_scc1 .LBB0_20
	s_mul_hi_i32 s6, s30, 0x2e8ba2e9
	s_lshr_b32 s7, s6, 31
	s_ashr_i32 s6, s6, 5
	s_add_i32 s7, s6, s7
	s_mul_i32 s6, s7, 0xb0
	s_sub_i32 s6, s30, s6
	s_bfe_i32 s8, s6, 0x10002
	s_lshr_b32 s9, s6, 1
	s_and_b32 s8, s8, 0x58
	s_and_b32 s9, s9, 0x7fffffc
	s_add_i32 s8, s8, s9
	s_and_b32 s6, s6, 3
	s_or_b32 s6, s8, s6
	s_lshl_b32 s6, s6, 5
	v_lshrrev_b32_e32 v0, 5, v178
	v_lshl_or_b32 v46, s7, 6, v0
	s_ashr_i32 s7, s6, 31
	s_lshl_b64 s[6:7], s[6:7], 2
	v_and_b32_e32 v0, 31, v179
	s_add_u32 s6, s18, s6
	s_addc_u32 s7, s19, s7
	v_lshlrev_b32_e32 v0, 2, v0
	v_mov_b32_e32 v1, 0
	v_lshl_add_u64 v[24:25], s[6:7], 0, v[0:1]
	s_movk_i32 s8, 0x5800
	v_or_b32_e32 v0, 2, v46
	v_mad_i64_i32 v[10:11], s[6:7], v0, s8, v[24:25]
	v_or_b32_e32 v0, 4, v46
	v_mad_i64_i32 v[12:13], s[6:7], v0, s8, v[24:25]
	v_or_b32_e32 v0, 6, v46
	v_mad_i64_i32 v[14:15], s[6:7], v0, s8, v[24:25]
	v_or_b32_e32 v0, 8, v46
	v_mad_i64_i32 v[16:17], s[6:7], v0, s8, v[24:25]
	v_or_b32_e32 v0, 10, v46
	v_mad_i64_i32 v[18:19], s[6:7], v0, s8, v[24:25]
	v_or_b32_e32 v0, 12, v46
	v_mad_i64_i32 v[8:9], s[6:7], v46, s8, v[24:25]
	v_mad_i64_i32 v[20:21], s[6:7], v0, s8, v[24:25]
	v_or_b32_e32 v0, 14, v46
	v_mad_i64_i32 v[22:23], s[6:7], v0, s8, v[24:25]
	global_load_dword v0, v[8:9], off nt
	global_load_dword v1, v[10:11], off nt
	global_load_dword v2, v[12:13], off nt
	global_load_dword v3, v[14:15], off nt
	global_load_dword v4, v[16:17], off nt
	global_load_dword v5, v[18:19], off nt
	global_load_dword v6, v[20:21], off nt
	global_load_dword v7, v[22:23], off nt
	v_or_b32_e32 v8, 16, v46
	v_mad_i64_i32 v[16:17], s[6:7], v8, s8, v[24:25]
	v_or_b32_e32 v8, 18, v46
	v_mad_i64_i32 v[18:19], s[6:7], v8, s8, v[24:25]
	v_or_b32_e32 v8, 20, v46
	v_mad_i64_i32 v[20:21], s[6:7], v8, s8, v[24:25]
	v_or_b32_e32 v8, 22, v46
	v_mad_i64_i32 v[22:23], s[6:7], v8, s8, v[24:25]
	v_or_b32_e32 v8, 24, v46
	v_mad_i64_i32 v[26:27], s[6:7], v8, s8, v[24:25]
	v_or_b32_e32 v8, 26, v46
	v_mad_i64_i32 v[28:29], s[6:7], v8, s8, v[24:25]
	v_or_b32_e32 v8, 28, v46
	v_mad_i64_i32 v[30:31], s[6:7], v8, s8, v[24:25]
	v_or_b32_e32 v8, 30, v46
	v_mad_i64_i32 v[32:33], s[6:7], v8, s8, v[24:25]
	global_load_dword v8, v[16:17], off nt
	global_load_dword v9, v[18:19], off nt
	global_load_dword v10, v[20:21], off nt
	global_load_dword v11, v[22:23], off nt
	global_load_dword v12, v[26:27], off nt
	global_load_dword v13, v[28:29], off nt
	global_load_dword v14, v[30:31], off nt
	global_load_dword v15, v[32:33], off nt
	v_or_b32_e32 v16, 32, v46
	v_mad_i64_i32 v[26:27], s[6:7], v16, s8, v[24:25]
	v_or_b32_e32 v16, 34, v46
	v_mad_i64_i32 v[28:29], s[6:7], v16, s8, v[24:25]
	v_or_b32_e32 v16, 36, v46
	v_mad_i64_i32 v[30:31], s[6:7], v16, s8, v[24:25]
	v_or_b32_e32 v16, 38, v46
	v_mad_i64_i32 v[32:33], s[6:7], v16, s8, v[24:25]
	v_or_b32_e32 v16, 40, v46
	v_mad_i64_i32 v[34:35], s[6:7], v16, s8, v[24:25]
	v_or_b32_e32 v16, 42, v46
	v_mad_i64_i32 v[36:37], s[6:7], v16, s8, v[24:25]
	v_or_b32_e32 v16, 44, v46
	v_mad_i64_i32 v[38:39], s[6:7], v16, s8, v[24:25]
	v_or_b32_e32 v16, 46, v46
	v_mad_i64_i32 v[40:41], s[6:7], v16, s8, v[24:25]
	global_load_dword v16, v[26:27], off nt
	global_load_dword v17, v[28:29], off nt
	global_load_dword v18, v[30:31], off nt
	global_load_dword v19, v[32:33], off nt
	global_load_dword v20, v[34:35], off nt
	global_load_dword v21, v[36:37], off nt
	global_load_dword v22, v[38:39], off nt
	global_load_dword v23, v[40:41], off nt
	v_or_b32_e32 v26, 48, v46
	v_mad_i64_i32 v[32:33], s[6:7], v26, s8, v[24:25]
	v_or_b32_e32 v26, 50, v46
	v_mad_i64_i32 v[34:35], s[6:7], v26, s8, v[24:25]
	v_or_b32_e32 v26, 52, v46
	v_mad_i64_i32 v[36:37], s[6:7], v26, s8, v[24:25]
	v_or_b32_e32 v26, 54, v46
	v_mad_i64_i32 v[38:39], s[6:7], v26, s8, v[24:25]
	v_or_b32_e32 v26, 56, v46
	v_mad_i64_i32 v[40:41], s[6:7], v26, s8, v[24:25]
	v_or_b32_e32 v26, 58, v46
	v_mad_i64_i32 v[42:43], s[6:7], v26, s8, v[24:25]
	v_or_b32_e32 v26, 60, v46
	v_mad_i64_i32 v[44:45], s[6:7], v26, s8, v[24:25]
	v_or_b32_e32 v26, 62, v46
	v_mad_i64_i32 v[46:47], s[6:7], v26, s8, v[24:25]
	global_load_dword v24, v[32:33], off nt
	global_load_dword v25, v[34:35], off nt
	global_load_dword v26, v[36:37], off nt
	global_load_dword v27, v[38:39], off nt
	global_load_dword v28, v[40:41], off nt
	global_load_dword v29, v[42:43], off nt
	global_load_dword v30, v[44:45], off nt
	global_load_dword v31, v[46:47], off nt
	s_andn2_b64 vcc, exec, s[4:5]
	s_load_dwordx2 s[4:5], s[0:1], 0x98
	s_waitcnt lgkmcnt(0)
	s_lshl_b32 s31, s4, 3
	s_cbranch_vccz .LBB0_21
	s_branch .LBB0_89

; __global__ void __launch_bounds__(NT, 2) hymba_fwd(Args args) {
;     ...
;         if (bid == 0) { const float* lg = args.in[7]; LBv[tid] = 1.0f / (1.0f + __expf(lg[512 + tid] - lg[tid])); }
;         __syncthreads();
.LBB0_148:
	s_cmp_eq_u32 s68, 0
	s_cbranch_scc0 .LBB0_150
	s_waitcnt vmcnt(31)
	v_lshlrev_b32_e32 v0, 2, v179
	s_waitcnt vmcnt(0)
	v_mov_b32_e32 v1, v91
	v_mov_b32_e32 v2, v92
	v_sub_f32_e32 v1, v1, v2
	v_mul_f32_e32 v1, 0x3fb8aa3b, v1
	v_exp_f32_e32 v1, v1
	s_nop 0
	v_add_f32_e32 v1, 1.0, v1
	v_div_scale_f32 v2, s[4:5], v1, v1, 1.0
	v_rcp_f32_e32 v3, v2
	v_div_scale_f32 v4, vcc, 1.0, v1, 1.0
	s_load_dwordx2 s[4:5], s[0:1], 0x80
	s_waitcnt lgkmcnt(0)
	v_fma_f32 v5, -v2, v3, 1.0
	v_fmac_f32_e32 v3, v5, v3
	v_mul_f32_e32 v5, v4, v3
	v_fma_f32 v6, -v2, v5, v4
	v_fmac_f32_e32 v5, v6, v3
	v_fma_f32 v2, -v2, v5, v4
	v_div_fmas_f32 v2, v2, v3, v5
	v_div_fixup_f32 v1, v2, v1, 1.0
	global_store_dword v0, v1, s[4:5]
	v_lshrrev_b32_e32 v2, 4, v179
	v_lshrrev_b32_e32 v3, 2, v2
	v_mul_u32_u24_e32 v6, 0x204000, v3
	v_and_b32_e32 v2, 3, v2
	v_lshl_add_u32 v6, v2, 10, v6
	v_and_b32_e32 v2, 15, v179
	v_lshl_add_u32 v6, v2, 5, v6
	v_add_u32_e32 v6, 0xce83000, v6
	v_mov_b32_e32 v2, 0
	v_mov_b32_e32 v3, 0
	v_mov_b32_e32 v4, 0
	v_mov_b32_e32 v5, 0
	global_store_dwordx4 v6, v[2:5], s[4:5]
	global_store_dwordx4 v6, v[2:5], s[4:5] offset:16
